# scan loop: output written without exec toggling (non-leader lanes write to an unused LDS area)
# speedup vs baseline: 1.0031x; 1.0014x over previous
; #define LAS __attribute__((address_space(3)))
; DEVINL void rwkv_scan(LAS unsigned char* lds, const bf16_t* Prwkv, const bf16_t* Aa, const bf16_t* Gg, const bf16_t* Uu, const float* w0v, const float* a0v, const float* mu, ...
;     ...
;           for (int cc = 0; cc < SEQ / CH; ++cc) {
;             {
;                 const LAS float* ib = IN + (cc & 1) * (6 * CH * 64); LAS float* ob = OUT + (cc & 1) * (CH * 64); const LAS float* sc_ = SC + (cc & 1) * (3 * CH);
;                 f32x4 Ka[2], Kb[2]; float Av0, Av1, Bv0, Bv1;
.Lscan_chunk:
	s_and_b32 s2, s30, 1
	s_mul_i32 s3, s2, 0xc000
	s_add_i32 s3, s3, 16
	s_lshl_b32 s16, s2, 13
	s_add_i32 s16, s16, 0x18010
	s_mul_i32 s17, s2, 0x180
	s_add_i32 s17, s17, 0x1c010
	v_add_u32_e32 v118, s3, v106
	v_add_u32_e32 v119, s3, v109
	v_add_u32_e32 v119, 0x6000, v119
	v_add_u32_e32 v120, s16, v109
	v_and_b32_e32 v134, 63, v215
	v_lshlrev_b32_e32 v134, 3, v134
	v_add_u32_e32 v134, 0x1e000, v134
	v_cndmask_b32_e64 v120, v134, v120, s[8:9]
	v_mov_b32_e32 v121, s17
	s_setprio 2
	ds_read_b128 v[2:5], v118 offset:32768
	ds_read_b128 v[6:9], v118 offset:32784
	ds_read_b128 v[10:13], v118 offset:0
	ds_read_b128 v[14:17], v118 offset:16
	s_mov_b32 s44, 0
.Lscan_iter:
	ds_read_b128 v[26:29], v118 offset:40960
	ds_read_b128 v[30:33], v118 offset:40976
	ds_read_b128 v[76:79], v118 offset:16384
	ds_read_b128 v[80:83], v118 offset:16400
	ds_read2_b32 v[34:35], v119 offset0:0 offset1:32
	ds_read2_b32 v[0:1], v121 offset0:0 offset1:32
	ds_read_b128 v[18:21], v118 offset:8192
	ds_read_b128 v[22:25], v118 offset:8208
	s_waitcnt lgkmcnt(8)
	v_pk_mul_f32 v[84:85], v[60:61], v[2:3] op_sel:[0,0] op_sel_hi:[1,0]
	v_pk_mul_f32 v[86:87], v[60:61], v[10:11] op_sel:[0,0] op_sel_hi:[1,0]
	v_pk_fma_f32 v[84:85], v[62:63], v[2:3], v[84:85] op_sel:[0,1,0] op_sel_hi:[1,1,1]
	v_pk_fma_f32 v[86:87], v[62:63], v[10:11], v[86:87] op_sel:[0,1,0] op_sel_hi:[1,1,1]
	v_pk_fma_f32 v[84:85], v[64:65], v[4:5], v[84:85] op_sel:[0,0,0] op_sel_hi:[1,0,1]
	v_pk_fma_f32 v[86:87], v[64:65], v[12:13], v[86:87] op_sel:[0,0,0] op_sel_hi:[1,0,1]
	v_pk_fma_f32 v[84:85], v[66:67], v[4:5], v[84:85] op_sel:[0,1,0] op_sel_hi:[1,1,1]
	v_pk_fma_f32 v[86:87], v[66:67], v[12:13], v[86:87] op_sel:[0,1,0] op_sel_hi:[1,1,1]
	v_pk_fma_f32 v[84:85], v[68:69], v[6:7], v[84:85] op_sel:[0,0,0] op_sel_hi:[1,0,1]
	v_pk_fma_f32 v[86:87], v[68:69], v[14:15], v[86:87] op_sel:[0,0,0] op_sel_hi:[1,0,1]
	v_pk_fma_f32 v[84:85], v[70:71], v[6:7], v[84:85] op_sel:[0,1,0] op_sel_hi:[1,1,1]
	v_pk_fma_f32 v[86:87], v[70:71], v[14:15], v[86:87] op_sel:[0,1,0] op_sel_hi:[1,1,1]
	v_pk_fma_f32 v[84:85], v[72:73], v[8:9], v[84:85] op_sel:[0,0,0] op_sel_hi:[1,0,1]
	v_pk_fma_f32 v[86:87], v[72:73], v[16:17], v[86:87] op_sel:[0,0,0] op_sel_hi:[1,0,1]
	v_pk_fma_f32 v[84:85], v[74:75], v[8:9], v[84:85] op_sel:[0,1,0] op_sel_hi:[1,1,1]
	v_pk_fma_f32 v[86:87], v[74:75], v[16:17], v[86:87] op_sel:[0,1,0] op_sel_hi:[1,1,1]
	s_nop 0
	v_add_f32_dpp v84, v84, v84 quad_perm:[1,0,3,2] row_mask:0xf bank_mask:0xf bound_ctrl:1
	v_add_f32_dpp v85, v85, v85 quad_perm:[1,0,3,2] row_mask:0xf bank_mask:0xf bound_ctrl:1
	v_add_f32_dpp v86, v86, v86 quad_perm:[1,0,3,2] row_mask:0xf bank_mask:0xf bound_ctrl:1
	v_add_f32_dpp v87, v87, v87 quad_perm:[1,0,3,2] row_mask:0xf bank_mask:0xf bound_ctrl:1
	v_add_f32_dpp v84, v84, v84 quad_perm:[2,3,0,1] row_mask:0xf bank_mask:0xf bound_ctrl:1
	v_add_f32_dpp v85, v85, v85 quad_perm:[2,3,0,1] row_mask:0xf bank_mask:0xf bound_ctrl:1
	v_add_f32_dpp v86, v86, v86 quad_perm:[2,3,0,1] row_mask:0xf bank_mask:0xf bound_ctrl:1
	v_add_f32_dpp v87, v87, v87 quad_perm:[2,3,0,1] row_mask:0xf bank_mask:0xf bound_ctrl:1
	v_add_f32_dpp v84, v84, v84 row_half_mirror row_mask:0xf bank_mask:0xf bound_ctrl:1
	v_add_f32_dpp v85, v85, v85 row_half_mirror row_mask:0xf bank_mask:0xf bound_ctrl:1
	v_add_f32_dpp v86, v86, v86 row_half_mirror row_mask:0xf bank_mask:0xf bound_ctrl:1
	v_add_f32_dpp v87, v87, v87 row_half_mirror row_mask:0xf bank_mask:0xf bound_ctrl:1
	ds_read_b128 v[2:5], v118 offset:33024
	ds_read_b128 v[6:9], v118 offset:33040
	ds_read_b128 v[10:13], v118 offset:256
	ds_read_b128 v[14:17], v118 offset:272
	s_waitcnt lgkmcnt(10)
	v_pk_mul_f32 v[114:115], v[26:27], v[84:85] op_sel:[0,0] op_sel_hi:[0,1] neg_lo:[0,1] neg_hi:[0,1]
	v_pk_mul_f32 v[116:117], v[26:27], v[84:85] op_sel:[1,0] op_sel_hi:[1,1] neg_lo:[0,1] neg_hi:[0,1]
	v_pk_mul_f32 v[122:123], v[28:29], v[84:85] op_sel:[0,0] op_sel_hi:[0,1] neg_lo:[0,1] neg_hi:[0,1]
	v_pk_mul_f32 v[124:125], v[28:29], v[84:85] op_sel:[1,0] op_sel_hi:[1,1] neg_lo:[0,1] neg_hi:[0,1]
	v_pk_mul_f32 v[126:127], v[30:31], v[84:85] op_sel:[0,0] op_sel_hi:[0,1] neg_lo:[0,1] neg_hi:[0,1]
	v_pk_mul_f32 v[128:129], v[30:31], v[84:85] op_sel:[1,0] op_sel_hi:[1,1] neg_lo:[0,1] neg_hi:[0,1]
	v_pk_mul_f32 v[130:131], v[32:33], v[84:85] op_sel:[0,0] op_sel_hi:[0,1] neg_lo:[0,1] neg_hi:[0,1]
	v_pk_mul_f32 v[132:133], v[32:33], v[84:85] op_sel:[1,0] op_sel_hi:[1,1] neg_lo:[0,1] neg_hi:[0,1]
	s_waitcnt lgkmcnt(7)
	v_pk_fma_f32 v[114:115], v[76:77], v[34:35], v[114:115] op_sel:[0,0,0] op_sel_hi:[0,1,1]
	v_pk_fma_f32 v[116:117], v[76:77], v[34:35], v[116:117] op_sel:[1,0,0] op_sel_hi:[1,1,1]
	v_pk_fma_f32 v[122:123], v[78:79], v[34:35], v[122:123] op_sel:[0,0,0] op_sel_hi:[0,1,1]
	v_pk_fma_f32 v[124:125], v[78:79], v[34:35], v[124:125] op_sel:[1,0,0] op_sel_hi:[1,1,1]
	v_pk_fma_f32 v[126:127], v[80:81], v[34:35], v[126:127] op_sel:[0,0,0] op_sel_hi:[0,1,1]
	v_pk_fma_f32 v[128:129], v[80:81], v[34:35], v[128:129] op_sel:[1,0,0] op_sel_hi:[1,1,1]
	v_pk_fma_f32 v[130:131], v[82:83], v[34:35], v[130:131] op_sel:[0,0,0] op_sel_hi:[0,1,1]
	v_pk_fma_f32 v[132:133], v[82:83], v[34:35], v[132:133] op_sel:[1,0,0] op_sel_hi:[1,1,1]
	s_waitcnt lgkmcnt(6)
	v_pk_fma_f32 v[86:87], v[84:85], v[0:1], v[86:87] op_sel:[0,0,0] op_sel_hi:[1,0,1] neg_lo:[1,0,0] neg_hi:[1,0,0]
	v_pk_fma_f32 v[86:87], v[34:35], v[0:1], v[86:87] op_sel:[0,1,0] op_sel_hi:[1,1,1]
	ds_write2_b32 v120, v86, v87 offset0:0 offset1:32
	s_waitcnt lgkmcnt(5)
	v_pk_fma_f32 v[60:61], v[60:61], v[18:19], v[114:115] op_sel:[0,0,0] op_sel_hi:[1,0,1]
	v_pk_fma_f32 v[62:63], v[62:63], v[18:19], v[116:117] op_sel:[0,1,0] op_sel_hi:[1,1,1]
	v_pk_fma_f32 v[64:65], v[64:65], v[20:21], v[122:123] op_sel:[0,0,0] op_sel_hi:[1,0,1]
	v_pk_fma_f32 v[66:67], v[66:67], v[20:21], v[124:125] op_sel:[0,1,0] op_sel_hi:[1,1,1]
	v_pk_fma_f32 v[68:69], v[68:69], v[22:23], v[126:127] op_sel:[0,0,0] op_sel_hi:[1,0,1]
	v_pk_fma_f32 v[70:71], v[70:71], v[22:23], v[128:129] op_sel:[0,1,0] op_sel_hi:[1,1,1]
	v_pk_fma_f32 v[72:73], v[72:73], v[24:25], v[130:131] op_sel:[0,0,0] op_sel_hi:[1,0,1]
	v_pk_fma_f32 v[74:75], v[74:75], v[24:25], v[132:133] op_sel:[0,1,0] op_sel_hi:[1,1,1]
	ds_read_b128 v[26:29], v118 offset:41216
	ds_read_b128 v[30:33], v118 offset:41232
	ds_read_b128 v[76:79], v118 offset:16640
	ds_read_b128 v[80:83], v118 offset:16656
	ds_read2_b32 v[34:35], v119 offset0:64 offset1:96
	ds_read2_b32 v[0:1], v121 offset0:1 offset1:33
	ds_read_b128 v[18:21], v118 offset:8448
	ds_read_b128 v[22:25], v118 offset:8464
	s_waitcnt lgkmcnt(8)
	v_pk_mul_f32 v[84:85], v[60:61], v[2:3] op_sel:[0,0] op_sel_hi:[1,0]
	v_pk_mul_f32 v[86:87], v[60:61], v[10:11] op_sel:[0,0] op_sel_hi:[1,0]
	v_pk_fma_f32 v[84:85], v[62:63], v[2:3], v[84:85] op_sel:[0,1,0] op_sel_hi:[1,1,1]
	v_pk_fma_f32 v[86:87], v[62:63], v[10:11], v[86:87] op_sel:[0,1,0] op_sel_hi:[1,1,1]
	v_pk_fma_f32 v[84:85], v[64:65], v[4:5], v[84:85] op_sel:[0,0,0] op_sel_hi:[1,0,1]
	v_pk_fma_f32 v[86:87], v[64:65], v[12:13], v[86:87] op_sel:[0,0,0] op_sel_hi:[1,0,1]
	v_pk_fma_f32 v[84:85], v[66:67], v[4:5], v[84:85] op_sel:[0,1,0] op_sel_hi:[1,1,1]
	v_pk_fma_f32 v[86:87], v[66:67], v[12:13], v[86:87] op_sel:[0,1,0] op_sel_hi:[1,1,1]
	v_pk_fma_f32 v[84:85], v[68:69], v[6:7], v[84:85] op_sel:[0,0,0] op_sel_hi:[1,0,1]
	v_pk_fma_f32 v[86:87], v[68:69], v[14:15], v[86:87] op_sel:[0,0,0] op_sel_hi:[1,0,1]
	v_pk_fma_f32 v[84:85], v[70:71], v[6:7], v[84:85] op_sel:[0,1,0] op_sel_hi:[1,1,1]
	v_pk_fma_f32 v[86:87], v[70:71], v[14:15], v[86:87] op_sel:[0,1,0] op_sel_hi:[1,1,1]
	v_pk_fma_f32 v[84:85], v[72:73], v[8:9], v[84:85] op_sel:[0,0,0] op_sel_hi:[1,0,1]
	v_pk_fma_f32 v[86:87], v[72:73], v[16:17], v[86:87] op_sel:[0,0,0] op_sel_hi:[1,0,1]
	v_pk_fma_f32 v[84:85], v[74:75], v[8:9], v[84:85] op_sel:[0,1,0] op_sel_hi:[1,1,1]
	v_pk_fma_f32 v[86:87], v[74:75], v[16:17], v[86:87] op_sel:[0,1,0] op_sel_hi:[1,1,1]
	s_nop 0
	v_add_f32_dpp v84, v84, v84 quad_perm:[1,0,3,2] row_mask:0xf bank_mask:0xf bound_ctrl:1
	v_add_f32_dpp v85, v85, v85 quad_perm:[1,0,3,2] row_mask:0xf bank_mask:0xf bound_ctrl:1
	v_add_f32_dpp v86, v86, v86 quad_perm:[1,0,3,2] row_mask:0xf bank_mask:0xf bound_ctrl:1
	v_add_f32_dpp v87, v87, v87 quad_perm:[1,0,3,2] row_mask:0xf bank_mask:0xf bound_ctrl:1
	v_add_f32_dpp v84, v84, v84 quad_perm:[2,3,0,1] row_mask:0xf bank_mask:0xf bound_ctrl:1
	v_add_f32_dpp v85, v85, v85 quad_perm:[2,3,0,1] row_mask:0xf bank_mask:0xf bound_ctrl:1
	v_add_f32_dpp v86, v86, v86 quad_perm:[2,3,0,1] row_mask:0xf bank_mask:0xf bound_ctrl:1
	v_add_f32_dpp v87, v87, v87 quad_perm:[2,3,0,1] row_mask:0xf bank_mask:0xf bound_ctrl:1
	v_add_f32_dpp v84, v84, v84 row_half_mirror row_mask:0xf bank_mask:0xf bound_ctrl:1
	v_add_f32_dpp v85, v85, v85 row_half_mirror row_mask:0xf bank_mask:0xf bound_ctrl:1
	v_add_f32_dpp v86, v86, v86 row_half_mirror row_mask:0xf bank_mask:0xf bound_ctrl:1
	v_add_f32_dpp v87, v87, v87 row_half_mirror row_mask:0xf bank_mask:0xf bound_ctrl:1
	ds_read_b128 v[2:5], v118 offset:33280
	ds_read_b128 v[6:9], v118 offset:33296
	ds_read_b128 v[10:13], v118 offset:512
	ds_read_b128 v[14:17], v118 offset:528
	s_waitcnt lgkmcnt(10)
	v_pk_mul_f32 v[114:115], v[26:27], v[84:85] op_sel:[0,0] op_sel_hi:[0,1] neg_lo:[0,1] neg_hi:[0,1]
	v_pk_mul_f32 v[116:117], v[26:27], v[84:85] op_sel:[1,0] op_sel_hi:[1,1] neg_lo:[0,1] neg_hi:[0,1]
	v_pk_mul_f32 v[122:123], v[28:29], v[84:85] op_sel:[0,0] op_sel_hi:[0,1] neg_lo:[0,1] neg_hi:[0,1]
	v_pk_mul_f32 v[124:125], v[28:29], v[84:85] op_sel:[1,0] op_sel_hi:[1,1] neg_lo:[0,1] neg_hi:[0,1]
	v_pk_mul_f32 v[126:127], v[30:31], v[84:85] op_sel:[0,0] op_sel_hi:[0,1] neg_lo:[0,1] neg_hi:[0,1]
	v_pk_mul_f32 v[128:129], v[30:31], v[84:85] op_sel:[1,0] op_sel_hi:[1,1] neg_lo:[0,1] neg_hi:[0,1]
	v_pk_mul_f32 v[130:131], v[32:33], v[84:85] op_sel:[0,0] op_sel_hi:[0,1] neg_lo:[0,1] neg_hi:[0,1]
	v_pk_mul_f32 v[132:133], v[32:33], v[84:85] op_sel:[1,0] op_sel_hi:[1,1] neg_lo:[0,1] neg_hi:[0,1]
	s_waitcnt lgkmcnt(7)
	v_pk_fma_f32 v[114:115], v[76:77], v[34:35], v[114:115] op_sel:[0,0,0] op_sel_hi:[0,1,1]
	v_pk_fma_f32 v[116:117], v[76:77], v[34:35], v[116:117] op_sel:[1,0,0] op_sel_hi:[1,1,1]
	v_pk_fma_f32 v[122:123], v[78:79], v[34:35], v[122:123] op_sel:[0,0,0] op_sel_hi:[0,1,1]
	v_pk_fma_f32 v[124:125], v[78:79], v[34:35], v[124:125] op_sel:[1,0,0] op_sel_hi:[1,1,1]
	v_pk_fma_f32 v[126:127], v[80:81], v[34:35], v[126:127] op_sel:[0,0,0] op_sel_hi:[0,1,1]
	v_pk_fma_f32 v[128:129], v[80:81], v[34:35], v[128:129] op_sel:[1,0,0] op_sel_hi:[1,1,1]
	v_pk_fma_f32 v[130:131], v[82:83], v[34:35], v[130:131] op_sel:[0,0,0] op_sel_hi:[0,1,1]
	v_pk_fma_f32 v[132:133], v[82:83], v[34:35], v[132:133] op_sel:[1,0,0] op_sel_hi:[1,1,1]
	s_waitcnt lgkmcnt(6)
	v_pk_fma_f32 v[86:87], v[84:85], v[0:1], v[86:87] op_sel:[0,0,0] op_sel_hi:[1,0,1] neg_lo:[1,0,0] neg_hi:[1,0,0]
	v_pk_fma_f32 v[86:87], v[34:35], v[0:1], v[86:87] op_sel:[0,1,0] op_sel_hi:[1,1,1]
	ds_write2_b32 v120, v86, v87 offset0:64 offset1:96
	s_waitcnt lgkmcnt(5)
	v_pk_fma_f32 v[60:61], v[60:61], v[18:19], v[114:115] op_sel:[0,0,0] op_sel_hi:[1,0,1]
	v_pk_fma_f32 v[62:63], v[62:63], v[18:19], v[116:117] op_sel:[0,1,0] op_sel_hi:[1,1,1]
	v_pk_fma_f32 v[64:65], v[64:65], v[20:21], v[122:123] op_sel:[0,0,0] op_sel_hi:[1,0,1]
	v_pk_fma_f32 v[66:67], v[66:67], v[20:21], v[124:125] op_sel:[0,1,0] op_sel_hi:[1,1,1]
	v_pk_fma_f32 v[68:69], v[68:69], v[22:23], v[126:127] op_sel:[0,0,0] op_sel_hi:[1,0,1]
	v_pk_fma_f32 v[70:71], v[70:71], v[22:23], v[128:129] op_sel:[0,1,0] op_sel_hi:[1,1,1]
	v_pk_fma_f32 v[72:73], v[72:73], v[24:25], v[130:131] op_sel:[0,0,0] op_sel_hi:[1,0,1]
	v_pk_fma_f32 v[74:75], v[74:75], v[24:25], v[132:133] op_sel:[0,1,0] op_sel_hi:[1,1,1]
	ds_read_b128 v[26:29], v118 offset:41472
	ds_read_b128 v[30:33], v118 offset:41488
	ds_read_b128 v[76:79], v118 offset:16896
	ds_read_b128 v[80:83], v118 offset:16912
	ds_read2_b32 v[34:35], v119 offset0:128 offset1:160
	ds_read2_b32 v[0:1], v121 offset0:2 offset1:34
	ds_read_b128 v[18:21], v118 offset:8704
	ds_read_b128 v[22:25], v118 offset:8720
	s_waitcnt lgkmcnt(8)
	v_pk_mul_f32 v[84:85], v[60:61], v[2:3] op_sel:[0,0] op_sel_hi:[1,0]
	v_pk_mul_f32 v[86:87], v[60:61], v[10:11] op_sel:[0,0] op_sel_hi:[1,0]
	v_pk_fma_f32 v[84:85], v[62:63], v[2:3], v[84:85] op_sel:[0,1,0] op_sel_hi:[1,1,1]
	v_pk_fma_f32 v[86:87], v[62:63], v[10:11], v[86:87] op_sel:[0,1,0] op_sel_hi:[1,1,1]
	v_pk_fma_f32 v[84:85], v[64:65], v[4:5], v[84:85] op_sel:[0,0,0] op_sel_hi:[1,0,1]
	v_pk_fma_f32 v[86:87], v[64:65], v[12:13], v[86:87] op_sel:[0,0,0] op_sel_hi:[1,0,1]
	v_pk_fma_f32 v[84:85], v[66:67], v[4:5], v[84:85] op_sel:[0,1,0] op_sel_hi:[1,1,1]
	v_pk_fma_f32 v[86:87], v[66:67], v[12:13], v[86:87] op_sel:[0,1,0] op_sel_hi:[1,1,1]
	v_pk_fma_f32 v[84:85], v[68:69], v[6:7], v[84:85] op_sel:[0,0,0] op_sel_hi:[1,0,1]
	v_pk_fma_f32 v[86:87], v[68:69], v[14:15], v[86:87] op_sel:[0,0,0] op_sel_hi:[1,0,1]
	v_pk_fma_f32 v[84:85], v[70:71], v[6:7], v[84:85] op_sel:[0,1,0] op_sel_hi:[1,1,1]
	v_pk_fma_f32 v[86:87], v[70:71], v[14:15], v[86:87] op_sel:[0,1,0] op_sel_hi:[1,1,1]
	v_pk_fma_f32 v[84:85], v[72:73], v[8:9], v[84:85] op_sel:[0,0,0] op_sel_hi:[1,0,1]
	v_pk_fma_f32 v[86:87], v[72:73], v[16:17], v[86:87] op_sel:[0,0,0] op_sel_hi:[1,0,1]
	v_pk_fma_f32 v[84:85], v[74:75], v[8:9], v[84:85] op_sel:[0,1,0] op_sel_hi:[1,1,1]
	v_pk_fma_f32 v[86:87], v[74:75], v[16:17], v[86:87] op_sel:[0,1,0] op_sel_hi:[1,1,1]
	s_nop 0
	v_add_f32_dpp v84, v84, v84 quad_perm:[1,0,3,2] row_mask:0xf bank_mask:0xf bound_ctrl:1
	v_add_f32_dpp v85, v85, v85 quad_perm:[1,0,3,2] row_mask:0xf bank_mask:0xf bound_ctrl:1
	v_add_f32_dpp v86, v86, v86 quad_perm:[1,0,3,2] row_mask:0xf bank_mask:0xf bound_ctrl:1
	v_add_f32_dpp v87, v87, v87 quad_perm:[1,0,3,2] row_mask:0xf bank_mask:0xf bound_ctrl:1
	v_add_f32_dpp v84, v84, v84 quad_perm:[2,3,0,1] row_mask:0xf bank_mask:0xf bound_ctrl:1
	v_add_f32_dpp v85, v85, v85 quad_perm:[2,3,0,1] row_mask:0xf bank_mask:0xf bound_ctrl:1
	v_add_f32_dpp v86, v86, v86 quad_perm:[2,3,0,1] row_mask:0xf bank_mask:0xf bound_ctrl:1
	v_add_f32_dpp v87, v87, v87 quad_perm:[2,3,0,1] row_mask:0xf bank_mask:0xf bound_ctrl:1
	v_add_f32_dpp v84, v84, v84 row_half_mirror row_mask:0xf bank_mask:0xf bound_ctrl:1
	v_add_f32_dpp v85, v85, v85 row_half_mirror row_mask:0xf bank_mask:0xf bound_ctrl:1
	v_add_f32_dpp v86, v86, v86 row_half_mirror row_mask:0xf bank_mask:0xf bound_ctrl:1
	v_add_f32_dpp v87, v87, v87 row_half_mirror row_mask:0xf bank_mask:0xf bound_ctrl:1
	ds_read_b128 v[2:5], v118 offset:33536
	ds_read_b128 v[6:9], v118 offset:33552
	ds_read_b128 v[10:13], v118 offset:768
	ds_read_b128 v[14:17], v118 offset:784
	s_waitcnt lgkmcnt(10)
	v_pk_mul_f32 v[114:115], v[26:27], v[84:85] op_sel:[0,0] op_sel_hi:[0,1] neg_lo:[0,1] neg_hi:[0,1]
	v_pk_mul_f32 v[116:117], v[26:27], v[84:85] op_sel:[1,0] op_sel_hi:[1,1] neg_lo:[0,1] neg_hi:[0,1]
	v_pk_mul_f32 v[122:123], v[28:29], v[84:85] op_sel:[0,0] op_sel_hi:[0,1] neg_lo:[0,1] neg_hi:[0,1]
	v_pk_mul_f32 v[124:125], v[28:29], v[84:85] op_sel:[1,0] op_sel_hi:[1,1] neg_lo:[0,1] neg_hi:[0,1]
	v_pk_mul_f32 v[126:127], v[30:31], v[84:85] op_sel:[0,0] op_sel_hi:[0,1] neg_lo:[0,1] neg_hi:[0,1]
	v_pk_mul_f32 v[128:129], v[30:31], v[84:85] op_sel:[1,0] op_sel_hi:[1,1] neg_lo:[0,1] neg_hi:[0,1]
	v_pk_mul_f32 v[130:131], v[32:33], v[84:85] op_sel:[0,0] op_sel_hi:[0,1] neg_lo:[0,1] neg_hi:[0,1]
	v_pk_mul_f32 v[132:133], v[32:33], v[84:85] op_sel:[1,0] op_sel_hi:[1,1] neg_lo:[0,1] neg_hi:[0,1]
	s_waitcnt lgkmcnt(7)
	v_pk_fma_f32 v[114:115], v[76:77], v[34:35], v[114:115] op_sel:[0,0,0] op_sel_hi:[0,1,1]
	v_pk_fma_f32 v[116:117], v[76:77], v[34:35], v[116:117] op_sel:[1,0,0] op_sel_hi:[1,1,1]
	v_pk_fma_f32 v[122:123], v[78:79], v[34:35], v[122:123] op_sel:[0,0,0] op_sel_hi:[0,1,1]
	v_pk_fma_f32 v[124:125], v[78:79], v[34:35], v[124:125] op_sel:[1,0,0] op_sel_hi:[1,1,1]
	v_pk_fma_f32 v[126:127], v[80:81], v[34:35], v[126:127] op_sel:[0,0,0] op_sel_hi:[0,1,1]
	v_pk_fma_f32 v[128:129], v[80:81], v[34:35], v[128:129] op_sel:[1,0,0] op_sel_hi:[1,1,1]
	v_pk_fma_f32 v[130:131], v[82:83], v[34:35], v[130:131] op_sel:[0,0,0] op_sel_hi:[0,1,1]
	v_pk_fma_f32 v[132:133], v[82:83], v[34:35], v[132:133] op_sel:[1,0,0] op_sel_hi:[1,1,1]
	s_waitcnt lgkmcnt(6)
	v_pk_fma_f32 v[86:87], v[84:85], v[0:1], v[86:87] op_sel:[0,0,0] op_sel_hi:[1,0,1] neg_lo:[1,0,0] neg_hi:[1,0,0]
	v_pk_fma_f32 v[86:87], v[34:35], v[0:1], v[86:87] op_sel:[0,1,0] op_sel_hi:[1,1,1]
	ds_write2_b32 v120, v86, v87 offset0:128 offset1:160
	s_waitcnt lgkmcnt(5)
; #define SCAN_LDK(X, X0, X1, s_) do { const LAS float* p_ = ib + (s_) * 64 + kp; \
;                     X[0] = *(const LAS f32x4*)(p_ + 4 * CH * 64); X[1] = *(const LAS f32x4*)(p_ + 4 * CH * 64 + 4); \
;                     X0 = ib[3 * CH * 64 + (s_) * 64 + v0]; X1 = ib[3 * CH * 64 + (s_) * 64 + v1]; } while (0)
; DEVINL void rwkv_scan(LAS unsigned char* lds, const bf16_t* Prwkv, const bf16_t* Aa, const bf16_t* Gg, const bf16_t* Uu, const float* w0v, const float* a0v, const float* mu, ...
;     ...
;                 __builtin_amdgcn_s_setprio(2);
;                 SCAN_LDK(Ka, Av0, Av1, 0);
; #pragma unroll 1
;                 for (int s = 0; s < CH; s += 2) {
;                     SCAN_STEP(Ka, Av0, Av1, s, SCAN_LDK(Kb, Bv0, Bv1, s + 1));
;                     const int sn = (s + 2 < CH) ? s + 2 : CH - 1;
;                     SCAN_STEP(Kb, Bv0, Bv1, s + 1, SCAN_LDK(Ka, Av0, Av1, sn));
;                 }
;                 __builtin_amdgcn_s_setprio(0);
;     ...
;             }
;             __syncthreads();
	v_pk_fma_f32 v[60:61], v[60:61], v[18:19], v[114:115] op_sel:[0,0,0] op_sel_hi:[1,0,1]
	v_pk_fma_f32 v[62:63], v[62:63], v[18:19], v[116:117] op_sel:[0,1,0] op_sel_hi:[1,1,1]
	v_pk_fma_f32 v[64:65], v[64:65], v[20:21], v[122:123] op_sel:[0,0,0] op_sel_hi:[1,0,1]
	v_pk_fma_f32 v[66:67], v[66:67], v[20:21], v[124:125] op_sel:[0,1,0] op_sel_hi:[1,1,1]
	v_pk_fma_f32 v[68:69], v[68:69], v[22:23], v[126:127] op_sel:[0,0,0] op_sel_hi:[1,0,1]
	v_pk_fma_f32 v[70:71], v[70:71], v[22:23], v[128:129] op_sel:[0,1,0] op_sel_hi:[1,1,1]
	v_pk_fma_f32 v[72:73], v[72:73], v[24:25], v[130:131] op_sel:[0,0,0] op_sel_hi:[1,0,1]
	v_pk_fma_f32 v[74:75], v[74:75], v[24:25], v[132:133] op_sel:[0,1,0] op_sel_hi:[1,1,1]
	ds_read_b128 v[26:29], v118 offset:41728
	ds_read_b128 v[30:33], v118 offset:41744
	ds_read_b128 v[76:79], v118 offset:17152
	ds_read_b128 v[80:83], v118 offset:17168
	ds_read2_b32 v[34:35], v119 offset0:192 offset1:224
	ds_read2_b32 v[0:1], v121 offset0:3 offset1:35
	ds_read_b128 v[18:21], v118 offset:8960
	ds_read_b128 v[22:25], v118 offset:8976
	s_waitcnt lgkmcnt(8)
	v_pk_mul_f32 v[84:85], v[60:61], v[2:3] op_sel:[0,0] op_sel_hi:[1,0]
	v_pk_mul_f32 v[86:87], v[60:61], v[10:11] op_sel:[0,0] op_sel_hi:[1,0]
	v_pk_fma_f32 v[84:85], v[62:63], v[2:3], v[84:85] op_sel:[0,1,0] op_sel_hi:[1,1,1]
	v_pk_fma_f32 v[86:87], v[62:63], v[10:11], v[86:87] op_sel:[0,1,0] op_sel_hi:[1,1,1]
	v_pk_fma_f32 v[84:85], v[64:65], v[4:5], v[84:85] op_sel:[0,0,0] op_sel_hi:[1,0,1]
	v_pk_fma_f32 v[86:87], v[64:65], v[12:13], v[86:87] op_sel:[0,0,0] op_sel_hi:[1,0,1]
	v_pk_fma_f32 v[84:85], v[66:67], v[4:5], v[84:85] op_sel:[0,1,0] op_sel_hi:[1,1,1]
	v_pk_fma_f32 v[86:87], v[66:67], v[12:13], v[86:87] op_sel:[0,1,0] op_sel_hi:[1,1,1]
	v_pk_fma_f32 v[84:85], v[68:69], v[6:7], v[84:85] op_sel:[0,0,0] op_sel_hi:[1,0,1]
	v_pk_fma_f32 v[86:87], v[68:69], v[14:15], v[86:87] op_sel:[0,0,0] op_sel_hi:[1,0,1]
	v_pk_fma_f32 v[84:85], v[70:71], v[6:7], v[84:85] op_sel:[0,1,0] op_sel_hi:[1,1,1]
	v_pk_fma_f32 v[86:87], v[70:71], v[14:15], v[86:87] op_sel:[0,1,0] op_sel_hi:[1,1,1]
	v_pk_fma_f32 v[84:85], v[72:73], v[8:9], v[84:85] op_sel:[0,0,0] op_sel_hi:[1,0,1]
	v_pk_fma_f32 v[86:87], v[72:73], v[16:17], v[86:87] op_sel:[0,0,0] op_sel_hi:[1,0,1]
	v_pk_fma_f32 v[84:85], v[74:75], v[8:9], v[84:85] op_sel:[0,1,0] op_sel_hi:[1,1,1]
	v_pk_fma_f32 v[86:87], v[74:75], v[16:17], v[86:87] op_sel:[0,1,0] op_sel_hi:[1,1,1]
	s_nop 0
	v_add_f32_dpp v84, v84, v84 quad_perm:[1,0,3,2] row_mask:0xf bank_mask:0xf bound_ctrl:1
	v_add_f32_dpp v85, v85, v85 quad_perm:[1,0,3,2] row_mask:0xf bank_mask:0xf bound_ctrl:1
	v_add_f32_dpp v86, v86, v86 quad_perm:[1,0,3,2] row_mask:0xf bank_mask:0xf bound_ctrl:1
	v_add_f32_dpp v87, v87, v87 quad_perm:[1,0,3,2] row_mask:0xf bank_mask:0xf bound_ctrl:1
	v_add_f32_dpp v84, v84, v84 quad_perm:[2,3,0,1] row_mask:0xf bank_mask:0xf bound_ctrl:1
	v_add_f32_dpp v85, v85, v85 quad_perm:[2,3,0,1] row_mask:0xf bank_mask:0xf bound_ctrl:1
	v_add_f32_dpp v86, v86, v86 quad_perm:[2,3,0,1] row_mask:0xf bank_mask:0xf bound_ctrl:1
	v_add_f32_dpp v87, v87, v87 quad_perm:[2,3,0,1] row_mask:0xf bank_mask:0xf bound_ctrl:1
	v_add_f32_dpp v84, v84, v84 row_half_mirror row_mask:0xf bank_mask:0xf bound_ctrl:1
	v_add_f32_dpp v85, v85, v85 row_half_mirror row_mask:0xf bank_mask:0xf bound_ctrl:1
	v_add_f32_dpp v86, v86, v86 row_half_mirror row_mask:0xf bank_mask:0xf bound_ctrl:1
	v_add_f32_dpp v87, v87, v87 row_half_mirror row_mask:0xf bank_mask:0xf bound_ctrl:1
	ds_read_b128 v[2:5], v118 offset:33792
	ds_read_b128 v[6:9], v118 offset:33808
	ds_read_b128 v[10:13], v118 offset:1024
	ds_read_b128 v[14:17], v118 offset:1040
	s_waitcnt lgkmcnt(10)
	v_pk_mul_f32 v[114:115], v[26:27], v[84:85] op_sel:[0,0] op_sel_hi:[0,1] neg_lo:[0,1] neg_hi:[0,1]
	v_pk_mul_f32 v[116:117], v[26:27], v[84:85] op_sel:[1,0] op_sel_hi:[1,1] neg_lo:[0,1] neg_hi:[0,1]
	v_pk_mul_f32 v[122:123], v[28:29], v[84:85] op_sel:[0,0] op_sel_hi:[0,1] neg_lo:[0,1] neg_hi:[0,1]
	v_pk_mul_f32 v[124:125], v[28:29], v[84:85] op_sel:[1,0] op_sel_hi:[1,1] neg_lo:[0,1] neg_hi:[0,1]
	v_pk_mul_f32 v[126:127], v[30:31], v[84:85] op_sel:[0,0] op_sel_hi:[0,1] neg_lo:[0,1] neg_hi:[0,1]
	v_pk_mul_f32 v[128:129], v[30:31], v[84:85] op_sel:[1,0] op_sel_hi:[1,1] neg_lo:[0,1] neg_hi:[0,1]
	v_pk_mul_f32 v[130:131], v[32:33], v[84:85] op_sel:[0,0] op_sel_hi:[0,1] neg_lo:[0,1] neg_hi:[0,1]
	v_pk_mul_f32 v[132:133], v[32:33], v[84:85] op_sel:[1,0] op_sel_hi:[1,1] neg_lo:[0,1] neg_hi:[0,1]
	s_waitcnt lgkmcnt(7)
	v_pk_fma_f32 v[114:115], v[76:77], v[34:35], v[114:115] op_sel:[0,0,0] op_sel_hi:[0,1,1]
	v_pk_fma_f32 v[116:117], v[76:77], v[34:35], v[116:117] op_sel:[1,0,0] op_sel_hi:[1,1,1]
	v_pk_fma_f32 v[122:123], v[78:79], v[34:35], v[122:123] op_sel:[0,0,0] op_sel_hi:[0,1,1]
	v_pk_fma_f32 v[124:125], v[78:79], v[34:35], v[124:125] op_sel:[1,0,0] op_sel_hi:[1,1,1]
	v_pk_fma_f32 v[126:127], v[80:81], v[34:35], v[126:127] op_sel:[0,0,0] op_sel_hi:[0,1,1]
	v_pk_fma_f32 v[128:129], v[80:81], v[34:35], v[128:129] op_sel:[1,0,0] op_sel_hi:[1,1,1]
	v_pk_fma_f32 v[130:131], v[82:83], v[34:35], v[130:131] op_sel:[0,0,0] op_sel_hi:[0,1,1]
	v_pk_fma_f32 v[132:133], v[82:83], v[34:35], v[132:133] op_sel:[1,0,0] op_sel_hi:[1,1,1]
	s_waitcnt lgkmcnt(6)
	v_pk_fma_f32 v[86:87], v[84:85], v[0:1], v[86:87] op_sel:[0,0,0] op_sel_hi:[1,0,1] neg_lo:[1,0,0] neg_hi:[1,0,0]
	v_pk_fma_f32 v[86:87], v[34:35], v[0:1], v[86:87] op_sel:[0,1,0] op_sel_hi:[1,1,1]
	ds_write2_b32 v120, v86, v87 offset0:192 offset1:224
	s_waitcnt lgkmcnt(5)
	v_pk_fma_f32 v[60:61], v[60:61], v[18:19], v[114:115] op_sel:[0,0,0] op_sel_hi:[1,0,1]
	v_pk_fma_f32 v[62:63], v[62:63], v[18:19], v[116:117] op_sel:[0,1,0] op_sel_hi:[1,1,1]
	v_pk_fma_f32 v[64:65], v[64:65], v[20:21], v[122:123] op_sel:[0,0,0] op_sel_hi:[1,0,1]
	v_pk_fma_f32 v[66:67], v[66:67], v[20:21], v[124:125] op_sel:[0,1,0] op_sel_hi:[1,1,1]
	v_pk_fma_f32 v[68:69], v[68:69], v[22:23], v[126:127] op_sel:[0,0,0] op_sel_hi:[1,0,1]
	v_pk_fma_f32 v[70:71], v[70:71], v[22:23], v[128:129] op_sel:[0,1,0] op_sel_hi:[1,1,1]
	v_pk_fma_f32 v[72:73], v[72:73], v[24:25], v[130:131] op_sel:[0,0,0] op_sel_hi:[1,0,1]
	v_pk_fma_f32 v[74:75], v[74:75], v[24:25], v[132:133] op_sel:[0,1,0] op_sel_hi:[1,1,1]
	v_add_u32_e32 v118, 0x400, v118
	v_add_u32_e32 v119, 0x400, v119
	v_add_u32_e32 v120, 0x400, v120
	v_add_u32_e32 v121, 16, v121
	s_add_i32 s44, s44, 1
	s_cmp_lt_u32 s44, 8
	s_cbranch_scc1 .Lscan_iter
	s_setprio 0
	s_add_i32 s30, s30, 1
	s_cmp_eq_u32 s30, 64
	s_waitcnt lgkmcnt(0)
	s_barrier
	s_cbranch_scc0 .Lscan_chunk
	s_branch .LBB0_1087
